# row-norm loops: xor-butterfly stages 1/2/4/8 done with v_add_f32_dpp (quad_perm/row_half_mirror/row_mirror, bit-identical) instead of ds_swizzle+lgkmcnt(0); on top of the gain-vector hoist + attention
# baseline (speedup 1.0000x reference)
.LBB0_52:
	global_load_dwordx4 v[16:19], v[12:13], off offset:-3072
	global_load_dwordx4 v[20:23], v[12:13], off offset:-2048
	global_load_dwordx4 v[24:27], v[12:13], off offset:-1024
	global_load_dwordx4 v[28:31], v[12:13], off
	global_load_dwordx4 v[32:35], v[4:5], off
	global_load_dwordx4 v[44:47], v[4:5], off offset:1024
	global_load_dwordx4 v[48:51], v[4:5], off offset:2048
	global_load_dwordx4 v[52:55], v[4:5], off offset:3072
	v_add_u32_e32 v9, s94, v9
	v_lshl_add_u64 v[12:13], v[12:13], 0, s[12:13]
	s_waitcnt vmcnt(4)
	v_mul_f32_e32 v14, v17, v17
	v_mul_f32_e32 v36, v19, v19
	s_waitcnt vmcnt(3)
	v_mul_f32_e32 v37, v21, v21
	v_mul_f32_e32 v38, v23, v23
	s_waitcnt vmcnt(2)
	v_mul_f32_e32 v39, v25, v25
	v_mul_f32_e32 v40, v27, v27
	v_fmac_f32_e32 v14, v16, v16
	v_fmac_f32_e32 v36, v18, v18
	v_fmac_f32_e32 v37, v20, v20
	v_fmac_f32_e32 v38, v22, v22
	s_waitcnt vmcnt(1)
	v_mul_f32_e32 v41, v29, v29
	v_mul_f32_e32 v42, v31, v31
	v_fmac_f32_e32 v39, v24, v24
	v_fmac_f32_e32 v40, v26, v26
	v_add_f32_e32 v14, v14, v36
	v_add_f32_e32 v36, v37, v38
	v_fmac_f32_e32 v41, v28, v28
	v_fmac_f32_e32 v42, v30, v30
	v_add_f32_e32 v37, v39, v40
	v_add_f32_e32 v14, v14, v36
	v_add_f32_e32 v38, v41, v42
	v_add_f32_e32 v14, v14, v37
	v_add_f32_e32 v14, v14, v38
	s_nop 1
	v_add_f32_dpp v14, v14, v14 quad_perm:[1,0,3,2] row_mask:0xf bank_mask:0xf
	s_nop 1
	v_add_f32_dpp v14, v14, v14 quad_perm:[2,3,0,1] row_mask:0xf bank_mask:0xf
	s_nop 1
	v_add_f32_dpp v14, v14, v14 row_half_mirror row_mask:0xf bank_mask:0xf
	s_nop 1
	v_add_f32_dpp v14, v14, v14 row_mirror row_mask:0xf bank_mask:0xf
	ds_swizzle_b32 v36, v14 offset:swizzle(SWAP,16)
	s_waitcnt lgkmcnt(0)
	v_add_f32_e32 v14, v14, v36
	v_mov_b32_e32 v36, v14
	s_nop 1
	v_permlane32_swap_b32_e32 v14, v36
	v_add_f32_e32 v14, v14, v36
	v_fmamk_f32 v14, v14, 0x3a800000, v3
	v_mul_f32_e32 v36, 0x4f800000, v14
	v_cmp_gt_f32_e32 vcc, s3, v14
	s_nop 1
	v_cndmask_b32_e32 v14, v14, v36, vcc
	v_sqrt_f32_e32 v36, v14
	s_nop 0
	v_add_u32_e32 v37, -1, v36
	v_add_u32_e32 v38, 1, v36
	v_fma_f32 v39, -v37, v36, v14
	v_fma_f32 v40, -v38, v36, v14
	v_cmp_ge_f32_e64 s[0:1], 0, v39
	s_nop 1
	v_cndmask_b32_e64 v36, v36, v37, s[0:1]
	v_cmp_lt_f32_e64 s[0:1], 0, v40
	s_nop 1
	v_cndmask_b32_e64 v36, v36, v38, s[0:1]
	v_mul_f32_e32 v37, 0x37800000, v36
	v_cndmask_b32_e32 v36, v36, v37, vcc
	v_cmp_class_f32_e32 vcc, v14, v7
	s_nop 1
	v_cndmask_b32_e32 v14, v36, v14, vcc
	v_div_scale_f32 v36, s[0:1], v14, v14, 1.0
	v_rcp_f32_e32 v38, v36
	v_div_scale_f32 v37, vcc, 1.0, v14, 1.0
	v_fma_f32 v39, -v36, v38, 1.0
	v_fmac_f32_e32 v38, v39, v38
	v_mul_f32_e32 v39, v37, v38
	v_fma_f32 v40, -v36, v39, v37
	v_fmac_f32_e32 v39, v40, v38
	v_fma_f32 v36, -v36, v39, v37
	v_div_fmas_f32 v36, v36, v38, v39
	v_div_fixup_f32 v14, v36, v14, 1.0
	v_mul_f32_e32 v16, v16, v14
	v_mul_f32_e32 v17, v17, v14
	v_mul_f32_e32 v18, v18, v14
	v_mul_f32_e32 v19, v19, v14
	s_waitcnt vmcnt(0)
	v_mul_f32_e32 v16, v32, v16
	v_mul_f32_e32 v17, v33, v17
	v_mul_f32_e32 v18, v34, v18
	v_mul_f32_e32 v19, v35, v19
	v_cvt_pk_bf16_f32 v16, v16, v17
	v_cvt_pk_bf16_f32 v17, v18, v19
	global_store_dwordx2 v[10:11], v[16:17], off
	v_mul_f32_e32 v20, v20, v14
	v_mul_f32_e32 v21, v21, v14
	v_mul_f32_e32 v22, v22, v14
	v_mul_f32_e32 v23, v23, v14
	v_cmp_lt_i32_e32 vcc, s16, v9
	s_or_b64 s[14:15], vcc, s[14:15]
	v_mul_f32_e32 v16, v44, v20
	v_mul_f32_e32 v17, v45, v21
	v_mul_f32_e32 v18, v46, v22
	v_mul_f32_e32 v19, v47, v23
	v_cvt_pk_bf16_f32 v16, v16, v17
	v_cvt_pk_bf16_f32 v17, v18, v19
	global_store_dwordx2 v[10:11], v[16:17], off offset:512
	v_mul_f32_e32 v20, v24, v14
	v_mul_f32_e32 v21, v25, v14
	v_mul_f32_e32 v22, v26, v14
	v_mul_f32_e32 v23, v27, v14
	v_mul_f32_e32 v16, v20, v48
	v_mul_f32_e32 v17, v21, v49
	v_mul_f32_e32 v18, v22, v50
	v_mul_f32_e32 v19, v23, v51
	v_cvt_pk_bf16_f32 v16, v16, v17
	v_cvt_pk_bf16_f32 v17, v18, v19
	global_store_dwordx2 v[10:11], v[16:17], off offset:1024
	v_mul_f32_e32 v20, v28, v14
	v_mul_f32_e32 v21, v29, v14
	v_mul_f32_e32 v22, v30, v14
	v_mul_f32_e32 v14, v31, v14
	v_mul_f32_e32 v16, v20, v52
	v_mul_f32_e32 v17, v21, v53
	v_mul_f32_e32 v18, v22, v54
	v_mul_f32_e32 v14, v14, v55
	v_cvt_pk_bf16_f32 v16, v16, v17
	v_cvt_pk_bf16_f32 v17, v18, v14
	global_store_dwordx2 v[10:11], v[16:17], off offset:1536
	v_lshl_add_u64 v[10:11], v[10:11], 0, s[6:7]
	s_andn2_b64 exec, exec, s[14:15]
	s_cbranch_execnz .LBB0_52

.LBB0_55:
	v_and_b32_e32 v13, 0x1ff, v6
	v_lshlrev_b32_e32 v2, 12, v13
	v_lshl_add_u64 v[32:33], v[4:5], 0, v[2:3]
	global_load_dwordx4 v[16:19], v[32:33], off
	global_load_dwordx4 v[20:23], v[32:33], off offset:1024
	global_load_dwordx4 v[24:27], v[32:33], off offset:2048
	global_load_dwordx4 v[28:31], v[32:33], off offset:3072
	v_ashrrev_i32_e32 v32, 9, v6
	v_lshlrev_b32_e32 v36, 10, v32
	v_ashrrev_i32_e32 v33, 31, v32
	v_ashrrev_i32_e32 v37, 31, v36
	v_lshlrev_b64 v[32:33], 20, v[32:33]
	v_mov_b32_e32 v35, v3
	v_lshlrev_b32_e32 v34, 11, v13
	v_lshl_add_u64 v[32:33], s[6:7], 0, v[32:33]
	v_lshl_add_u64 v[36:37], v[36:37], 2, v[10:11]
	v_lshl_add_u64 v[38:39], v[32:33], 0, v[34:35]
	global_load_dwordx4 v[32:35], v[36:37], off
	global_load_dwordx4 v[48:51], v[36:37], off offset:1024
	global_load_dwordx4 v[52:55], v[36:37], off offset:2048
	global_load_dwordx4 v[56:59], v[36:37], off offset:3072
	v_lshl_add_u64 v[38:39], v[38:39], 0, v[8:9]
	v_add_u32_e32 v6, s94, v6
	s_waitcnt vmcnt(4)
	v_mul_f32_e32 v2, v17, v17
	v_mul_f32_e32 v13, v19, v19
	s_waitcnt vmcnt(3)
	v_mul_f32_e32 v14, v21, v21
	v_mul_f32_e32 v40, v23, v23
	s_waitcnt vmcnt(2)
	v_mul_f32_e32 v41, v25, v25
	v_mul_f32_e32 v42, v27, v27
	v_fmac_f32_e32 v2, v16, v16
	v_fmac_f32_e32 v13, v18, v18
	v_fmac_f32_e32 v14, v20, v20
	v_fmac_f32_e32 v40, v22, v22
	s_waitcnt vmcnt(1)
	v_mul_f32_e32 v43, v29, v29
	v_mul_f32_e32 v44, v31, v31
	v_fmac_f32_e32 v41, v24, v24
	v_fmac_f32_e32 v42, v26, v26
	v_add_f32_e32 v2, v2, v13
	v_add_f32_e32 v13, v14, v40
	v_fmac_f32_e32 v43, v28, v28
	v_fmac_f32_e32 v44, v30, v30
	v_add_f32_e32 v14, v41, v42
	v_add_f32_e32 v2, v2, v13
	v_add_f32_e32 v40, v43, v44
	v_add_f32_e32 v2, v2, v14
	v_add_f32_e32 v2, v2, v40
	s_nop 1
	v_add_f32_dpp v2, v2, v2 quad_perm:[1,0,3,2] row_mask:0xf bank_mask:0xf
	s_nop 1
	v_add_f32_dpp v2, v2, v2 quad_perm:[2,3,0,1] row_mask:0xf bank_mask:0xf
	s_nop 1
	v_add_f32_dpp v2, v2, v2 row_half_mirror row_mask:0xf bank_mask:0xf
	s_nop 1
	v_add_f32_dpp v2, v2, v2 row_mirror row_mask:0xf bank_mask:0xf
	ds_swizzle_b32 v13, v2 offset:swizzle(SWAP,16)
	s_waitcnt lgkmcnt(0)
	v_add_f32_e32 v2, v2, v13
	v_mov_b32_e32 v13, v2
	s_nop 1
	v_permlane32_swap_b32_e32 v2, v13
	v_add_f32_e32 v2, v2, v13
	v_fmamk_f32 v2, v2, 0x3a800000, v7
	v_mul_f32_e32 v13, 0x4f800000, v2
	v_cmp_gt_f32_e32 vcc, s3, v2
	s_nop 1
	v_cndmask_b32_e32 v2, v2, v13, vcc
	v_sqrt_f32_e32 v13, v2
	s_nop 0
	v_add_u32_e32 v14, -1, v13
	v_add_u32_e32 v40, 1, v13
	v_fma_f32 v41, -v14, v13, v2
	v_fma_f32 v42, -v40, v13, v2
	v_cmp_ge_f32_e64 s[0:1], 0, v41
	s_nop 1
	v_cndmask_b32_e64 v13, v13, v14, s[0:1]
	v_cmp_lt_f32_e64 s[0:1], 0, v42
	s_nop 1
	v_cndmask_b32_e64 v13, v13, v40, s[0:1]
	v_mul_f32_e32 v14, 0x37800000, v13
	v_cndmask_b32_e32 v13, v13, v14, vcc
	v_cmp_class_f32_e32 vcc, v2, v12
	s_nop 1
	v_cndmask_b32_e32 v2, v13, v2, vcc
	v_div_scale_f32 v13, s[0:1], v2, v2, 1.0
	v_rcp_f32_e32 v40, v13
	v_div_scale_f32 v14, vcc, 1.0, v2, 1.0
	v_fma_f32 v41, -v13, v40, 1.0
	v_fmac_f32_e32 v40, v41, v40
	v_mul_f32_e32 v41, v14, v40
	v_fma_f32 v42, -v13, v41, v14
	v_fmac_f32_e32 v41, v42, v40
	v_fma_f32 v13, -v13, v41, v14
	v_div_fmas_f32 v13, v13, v40, v41
	v_div_fixup_f32 v2, v13, v2, 1.0
	v_mul_f32_e32 v14, v17, v2
	v_mul_f32_e32 v17, v19, v2
	v_mul_f32_e32 v13, v16, v2
	v_mul_f32_e32 v16, v18, v2
	s_waitcnt vmcnt(0)
	v_mul_f32_e32 v17, v35, v17
	v_mul_f32_e32 v13, v32, v13
	v_mul_f32_e32 v14, v33, v14
	v_mul_f32_e32 v18, v34, v16
	v_cvt_pk_bf16_f32 v16, v13, v14
	v_cvt_pk_bf16_f32 v17, v18, v17
	global_store_dwordx2 v[38:39], v[16:17], off
	v_mul_f32_e32 v13, v20, v2
	v_mul_f32_e32 v14, v21, v2
	v_mul_f32_e32 v20, v22, v2
	v_mul_f32_e32 v21, v23, v2
	v_cmp_lt_i32_e32 vcc, s14, v6
	s_or_b64 s[12:13], vcc, s[12:13]
	v_mul_f32_e32 v14, v49, v14
	v_mul_f32_e32 v17, v50, v20
	v_mul_f32_e32 v13, v48, v13
	v_mul_f32_e32 v18, v51, v21
	v_cvt_pk_bf16_f32 v16, v13, v14
	v_cvt_pk_bf16_f32 v17, v17, v18
	global_store_dwordx2 v[38:39], v[16:17], off offset:512
	v_mul_f32_e32 v14, v25, v2
	v_mul_f32_e32 v20, v26, v2
	v_mul_f32_e32 v13, v24, v2
	v_mul_f32_e32 v21, v27, v2
	v_mul_f32_e32 v14, v14, v53
	v_mul_f32_e32 v17, v20, v54
	v_mul_f32_e32 v13, v13, v52
	v_mul_f32_e32 v18, v21, v55
	v_cvt_pk_bf16_f32 v16, v13, v14
	v_cvt_pk_bf16_f32 v17, v17, v18
	global_store_dwordx2 v[38:39], v[16:17], off offset:1024
	v_mul_f32_e32 v14, v29, v2
	v_mul_f32_e32 v20, v30, v2
	v_mul_f32_e32 v13, v28, v2
	v_mul_f32_e32 v2, v31, v2
	v_mul_f32_e32 v14, v14, v57
	v_mul_f32_e32 v17, v20, v58
	v_mul_f32_e32 v13, v13, v56
	v_mul_f32_e32 v2, v2, v59
	v_cvt_pk_bf16_f32 v16, v13, v14
	v_cvt_pk_bf16_f32 v17, v17, v2
	global_store_dwordx2 v[38:39], v[16:17], off offset:1536
	s_andn2_b64 exec, exec, s[12:13]
	s_cbranch_execnz .LBB0_55

.LBB0_137:
	v_ashrrev_i32_e32 v1, 31, v0
	v_lshlrev_b64 v[8:9], 12, v[0:1]
	v_lshl_add_u64 v[20:21], v[2:3], 0, v[8:9]
	global_load_dwordx4 v[8:11], v[20:21], off
	global_load_dwordx4 v[12:15], v[20:21], off offset:1024
	global_load_dwordx4 v[16:19], v[20:21], off offset:2048
	s_nop 0
	global_load_dwordx4 v[20:23], v[20:21], off offset:3072
	s_nop 0
	global_load_dwordx4 v[24:27], v[4:5], off
	global_load_dwordx4 v[40:43], v[4:5], off offset:1024
	global_load_dwordx4 v[44:47], v[4:5], off offset:2048
	global_load_dwordx4 v[48:51], v[4:5], off offset:3072
	s_waitcnt vmcnt(0)
	v_mul_f32_e32 v28, v9, v9
	v_mul_f32_e32 v29, v11, v11
	s_waitcnt vmcnt(3)
	v_mul_f32_e32 v30, v13, v13
	v_mul_f32_e32 v31, v15, v15
	s_waitcnt vmcnt(2)
	v_mul_f32_e32 v32, v17, v17
	v_mul_f32_e32 v33, v19, v19
	v_fmac_f32_e32 v28, v8, v8
	v_fmac_f32_e32 v29, v10, v10
	v_fmac_f32_e32 v30, v12, v12
	v_fmac_f32_e32 v31, v14, v14
	s_waitcnt vmcnt(1)
	v_mul_f32_e32 v34, v21, v21
	v_mul_f32_e32 v35, v23, v23
	v_fmac_f32_e32 v32, v16, v16
	v_fmac_f32_e32 v33, v18, v18
	v_add_f32_e32 v28, v28, v29
	v_add_f32_e32 v29, v30, v31
	v_fmac_f32_e32 v34, v20, v20
	v_fmac_f32_e32 v35, v22, v22
	v_add_f32_e32 v30, v32, v33
	v_add_f32_e32 v28, v28, v29
	v_add_f32_e32 v31, v34, v35
	v_add_f32_e32 v28, v28, v30
	v_add_f32_e32 v28, v28, v31
	s_nop 1
	v_add_f32_dpp v28, v28, v28 quad_perm:[1,0,3,2] row_mask:0xf bank_mask:0xf
	s_nop 1
	v_add_f32_dpp v28, v28, v28 quad_perm:[2,3,0,1] row_mask:0xf bank_mask:0xf
	s_nop 1
	v_add_f32_dpp v28, v28, v28 row_half_mirror row_mask:0xf bank_mask:0xf
	s_nop 1
	v_add_f32_dpp v28, v28, v28 row_mirror row_mask:0xf bank_mask:0xf
	ds_swizzle_b32 v29, v28 offset:swizzle(SWAP,16)
	s_waitcnt lgkmcnt(0)
	v_add_f32_e32 v28, v28, v29
	v_mov_b32_e32 v29, v28
	s_nop 1
	v_permlane32_swap_b32_e32 v28, v29
	v_add_f32_e32 v28, v28, v29
	v_fmamk_f32 v28, v28, 0x3a800000, v163
	v_mul_f32_e32 v29, 0x4f800000, v28
	v_cmp_gt_f32_e32 vcc, s27, v28
	s_nop 1
	v_cndmask_b32_e32 v30, v28, v29, vcc
	v_sqrt_f32_e32 v31, v30
	v_lshlrev_b64 v[28:29], 11, v[0:1]
	v_lshl_add_u64 v[28:29], v[6:7], 0, v[28:29]
	v_add_u32_e32 v0, s94, v0
	v_add_u32_e32 v1, -1, v31
	v_add_u32_e32 v32, 1, v31
	v_fma_f32 v33, -v1, v31, v30
	v_fma_f32 v34, -v32, v31, v30
	v_cmp_ge_f32_e64 s[34:35], 0, v33
	s_nop 1
	v_cndmask_b32_e64 v1, v31, v1, s[34:35]
	v_cmp_lt_f32_e64 s[34:35], 0, v34
	s_nop 1
	v_cndmask_b32_e64 v1, v1, v32, s[34:35]
	v_mul_f32_e32 v31, 0x37800000, v1
	v_cndmask_b32_e32 v1, v1, v31, vcc
	v_cmp_class_f32_e32 vcc, v30, v204
	s_nop 1
	v_cndmask_b32_e32 v1, v1, v30, vcc
	v_div_scale_f32 v30, s[0:1], v1, v1, 1.0
	v_rcp_f32_e32 v31, v30
	v_div_scale_f32 v32, vcc, 1.0, v1, 1.0
	s_movk_i32 s0, 0x3fff
	v_fma_f32 v33, -v30, v31, 1.0
	v_fmac_f32_e32 v31, v33, v31
	v_mul_f32_e32 v33, v32, v31
	v_fma_f32 v34, -v30, v33, v32
	v_fmac_f32_e32 v33, v34, v31
	v_fma_f32 v30, -v30, v33, v32
	v_div_fmas_f32 v30, v30, v31, v33
	v_div_fixup_f32 v1, v30, v1, 1.0
	v_mul_f32_e32 v8, v8, v1
	v_mul_f32_e32 v9, v9, v1
	v_mul_f32_e32 v10, v10, v1
	v_mul_f32_e32 v11, v11, v1
	s_waitcnt vmcnt(0)
	v_mul_f32_e32 v8, v24, v8
	v_mul_f32_e32 v9, v25, v9
	v_mul_f32_e32 v10, v26, v10
	v_mul_f32_e32 v11, v27, v11
	v_cvt_pk_bf16_f32 v8, v8, v9
	v_cvt_pk_bf16_f32 v9, v10, v11
	global_store_dwordx2 v[28:29], v[8:9], off
	v_mul_f32_e32 v12, v12, v1
	v_mul_f32_e32 v13, v13, v1
	v_mul_f32_e32 v14, v14, v1
	v_mul_f32_e32 v15, v15, v1
	v_cmp_lt_i32_e32 vcc, s0, v0
	s_or_b64 s[18:19], vcc, s[18:19]
	v_mul_f32_e32 v8, v40, v12
	v_mul_f32_e32 v9, v41, v13
	v_mul_f32_e32 v10, v42, v14
	v_mul_f32_e32 v11, v43, v15
	v_cvt_pk_bf16_f32 v8, v8, v9
	v_cvt_pk_bf16_f32 v9, v10, v11
	global_store_dwordx2 v[28:29], v[8:9], off offset:512
	v_mul_f32_e32 v12, v16, v1
	v_mul_f32_e32 v13, v17, v1
	v_mul_f32_e32 v14, v18, v1
	v_mul_f32_e32 v15, v19, v1
	v_mul_f32_e32 v8, v12, v44
	v_mul_f32_e32 v9, v13, v45
	v_mul_f32_e32 v10, v14, v46
	v_mul_f32_e32 v11, v15, v47
	v_cvt_pk_bf16_f32 v8, v8, v9
	v_cvt_pk_bf16_f32 v9, v10, v11
	global_store_dwordx2 v[28:29], v[8:9], off offset:1024
	v_mul_f32_e32 v12, v20, v1
	v_mul_f32_e32 v13, v21, v1
	v_mul_f32_e32 v14, v22, v1
	v_mul_f32_e32 v1, v23, v1
	v_mul_f32_e32 v8, v12, v48
	v_mul_f32_e32 v9, v13, v49
	v_mul_f32_e32 v10, v14, v50
	v_mul_f32_e32 v1, v1, v51
	v_cvt_pk_bf16_f32 v8, v8, v9
	v_cvt_pk_bf16_f32 v9, v10, v1
	global_store_dwordx2 v[28:29], v[8:9], off offset:1536
	s_andn2_b64 exec, exec, s[18:19]
	s_cbranch_execnz .LBB0_137

.LBB0_512:
	v_ashrrev_i32_e32 v23, 31, v22
	v_lshlrev_b64 v[2:3], 12, v[22:23]
	v_lshl_add_u64 v[28:29], v[24:25], 0, v[2:3]
	global_load_dwordx4 v[2:5], v[28:29], off
	v_add_u32_e32 v22, s94, v22
	s_waitcnt vmcnt(0)
	v_mul_f32_e32 v0, v3, v3
	v_mul_f32_e32 v6, v5, v5
	v_fmac_f32_e32 v0, v2, v2
	v_fmac_f32_e32 v6, v4, v4
	v_add_f32_e32 v0, v0, v6
	global_load_dwordx4 v[6:9], v[28:29], off offset:1024
	s_waitcnt vmcnt(0)
	v_mul_f32_e32 v10, v7, v7
	v_mul_f32_e32 v11, v9, v9
	v_fmac_f32_e32 v10, v6, v6
	v_fmac_f32_e32 v11, v8, v8
	v_add_f32_e32 v10, v10, v11
	v_add_f32_e32 v0, v0, v10
	global_load_dwordx4 v[10:13], v[28:29], off offset:2048
	s_waitcnt vmcnt(0)
	v_mul_f32_e32 v14, v11, v11
	v_mul_f32_e32 v15, v13, v13
	v_fmac_f32_e32 v14, v10, v10
	v_fmac_f32_e32 v15, v12, v12
	v_add_f32_e32 v14, v14, v15
	v_add_f32_e32 v0, v0, v14
	global_load_dwordx4 v[14:17], v[28:29], off offset:3072
	s_waitcnt vmcnt(0)
	v_mul_f32_e32 v18, v15, v15
	v_mul_f32_e32 v19, v17, v17
	v_fmac_f32_e32 v18, v14, v14
	v_fmac_f32_e32 v19, v16, v16
	v_add_f32_e32 v18, v18, v19
	v_add_f32_e32 v0, v0, v18
	s_nop 1
	v_add_f32_dpp v0, v0, v0 quad_perm:[1,0,3,2] row_mask:0xf bank_mask:0xf
	s_nop 1
	v_add_f32_dpp v0, v0, v0 quad_perm:[2,3,0,1] row_mask:0xf bank_mask:0xf
	s_nop 1
	v_add_f32_dpp v0, v0, v0 row_half_mirror row_mask:0xf bank_mask:0xf
	s_nop 1
	v_add_f32_dpp v0, v0, v0 row_mirror row_mask:0xf bank_mask:0xf
	ds_swizzle_b32 v18, v0 offset:swizzle(SWAP,16)
	s_waitcnt lgkmcnt(0)
	v_add_f32_e32 v0, v0, v18
	v_mov_b32_e32 v18, v0
	s_nop 1
	v_permlane32_swap_b32_e32 v0, v18
	v_add_f32_e32 v0, v0, v18
	v_fmamk_f32 v0, v0, 0x3a800000, v229
	v_cmp_gt_f32_e32 vcc, s87, v0
	v_mul_f32_e32 v18, 0x4f800000, v0
	s_nop 0
	v_cndmask_b32_e32 v0, v0, v18, vcc
	v_sqrt_f32_e32 v18, v0
	s_nop 0
	v_add_u32_e32 v19, -1, v18
	v_fma_f32 v20, -v19, v18, v0
	v_cmp_ge_f32_e64 s[38:39], 0, v20
	v_add_u32_e32 v20, 1, v18
	s_nop 0
	v_cndmask_b32_e64 v19, v18, v19, s[38:39]
	v_fma_f32 v18, -v20, v18, v0
	v_cmp_lt_f32_e64 s[38:39], 0, v18
	s_nop 1
	v_cndmask_b32_e64 v18, v19, v20, s[38:39]
	v_mul_f32_e32 v19, 0x37800000, v18
	v_cndmask_b32_e32 v18, v18, v19, vcc
	v_cmp_class_f32_e32 vcc, v0, v230
	s_nop 1
	v_cndmask_b32_e32 v0, v18, v0, vcc
	v_div_scale_f32 v18, s[0:1], v0, v0, 1.0
	v_rcp_f32_e32 v19, v18
	s_movk_i32 s0, 0x3fff
	v_fma_f32 v20, -v18, v19, 1.0
	v_fmac_f32_e32 v19, v20, v19
	v_div_scale_f32 v20, vcc, 1.0, v0, 1.0
	v_mul_f32_e32 v21, v20, v19
	v_fma_f32 v23, -v18, v21, v20
	v_fmac_f32_e32 v21, v23, v19
	v_fma_f32 v18, -v18, v21, v20
	v_div_fmas_f32 v18, v18, v19, v21
	v_div_fixup_f32 v0, v18, v0, 1.0
	global_load_dwordx4 v[18:21], v[26:27], off
	global_load_dwordx4 v[40:43], v[26:27], off offset:1024
	global_load_dwordx4 v[44:47], v[26:27], off offset:2048
	global_load_dwordx4 v[48:51], v[26:27], off offset:3072
	v_pk_mul_f32 v[2:3], v[2:3], v[0:1] op_sel_hi:[1,0]
	v_pk_mul_f32 v[4:5], v[4:5], v[0:1] op_sel_hi:[1,0]
	v_pk_mul_f32 v[8:9], v[8:9], v[0:1] op_sel_hi:[1,0]
	v_pk_mul_f32 v[6:7], v[6:7], v[0:1] op_sel_hi:[1,0]
	v_cmp_lt_i32_e32 vcc, s0, v22
	s_or_b64 s[24:25], vcc, s[24:25]
	s_waitcnt vmcnt(0)
	v_pk_mul_f32 v[4:5], v[20:21], v[4:5]
	v_pk_mul_f32 v[2:3], v[18:19], v[2:3]
	global_store_dwordx4 v[28:29], v[2:5], off
	s_nop 1
	v_pk_mul_f32 v[2:3], v[40:41], v[6:7]
	v_pk_mul_f32 v[4:5], v[42:43], v[8:9]
	global_store_dwordx4 v[28:29], v[2:5], off offset:1024
	v_pk_mul_f32 v[6:7], v[12:13], v[0:1] op_sel_hi:[1,0]
	v_pk_mul_f32 v[8:9], v[10:11], v[0:1] op_sel_hi:[1,0]
	v_pk_mul_f32 v[4:5], v[46:47], v[6:7]
	v_pk_mul_f32 v[2:3], v[44:45], v[8:9]
	global_store_dwordx4 v[28:29], v[2:5], off offset:2048
	v_pk_mul_f32 v[6:7], v[16:17], v[0:1] op_sel_hi:[1,0]
	v_pk_mul_f32 v[8:9], v[14:15], v[0:1] op_sel_hi:[1,0]
	v_pk_mul_f32 v[4:5], v[50:51], v[6:7]
	v_pk_mul_f32 v[2:3], v[48:49], v[8:9]
	global_store_dwordx4 v[28:29], v[2:5], off offset:3072
	s_andn2_b64 exec, exec, s[24:25]
	s_cbranch_execnz .LBB0_512

.LBB0_517:
	v_ashrrev_i32_e32 v23, 31, v22
	v_lshlrev_b64 v[2:3], 12, v[22:23]
	v_lshl_add_u64 v[6:7], v[24:25], 0, v[2:3]
	global_load_dwordx4 v[14:17], v[6:7], off
	global_load_dwordx4 v[10:13], v[6:7], off offset:1024
	s_waitcnt vmcnt(0)
	v_mul_f32_e32 v0, v15, v15
	v_mul_f32_e32 v2, v17, v17
	v_fmac_f32_e32 v0, v14, v14
	v_fmac_f32_e32 v2, v16, v16
	v_add_f32_e32 v0, v0, v2
	s_waitcnt vmcnt(0)
	v_mul_f32_e32 v2, v11, v11
	v_mul_f32_e32 v3, v13, v13
	v_fmac_f32_e32 v2, v10, v10
	v_fmac_f32_e32 v3, v12, v12
	v_add_f32_e32 v2, v2, v3
	v_add_f32_e32 v0, v0, v2
	global_load_dwordx4 v[2:5], v[6:7], off offset:2048
	s_waitcnt vmcnt(0)
	v_mul_f32_e32 v8, v3, v3
	v_mul_f32_e32 v9, v5, v5
	v_fmac_f32_e32 v8, v2, v2
	v_fmac_f32_e32 v9, v4, v4
	v_add_f32_e32 v8, v8, v9
	v_add_f32_e32 v0, v0, v8
	global_load_dwordx4 v[6:9], v[6:7], off offset:3072
	s_waitcnt vmcnt(0)
	v_mul_f32_e32 v18, v7, v7
	v_mul_f32_e32 v19, v9, v9
	v_fmac_f32_e32 v18, v6, v6
	v_fmac_f32_e32 v19, v8, v8
	v_add_f32_e32 v18, v18, v19
	v_add_f32_e32 v0, v0, v18
	s_nop 1
	v_add_f32_dpp v0, v0, v0 quad_perm:[1,0,3,2] row_mask:0xf bank_mask:0xf
	s_nop 1
	v_add_f32_dpp v0, v0, v0 quad_perm:[2,3,0,1] row_mask:0xf bank_mask:0xf
	s_nop 1
	v_add_f32_dpp v0, v0, v0 row_half_mirror row_mask:0xf bank_mask:0xf
	s_nop 1
	v_add_f32_dpp v0, v0, v0 row_mirror row_mask:0xf bank_mask:0xf
	ds_swizzle_b32 v18, v0 offset:swizzle(SWAP,16)
	s_waitcnt lgkmcnt(0)
	v_add_f32_e32 v0, v0, v18
	v_mov_b32_e32 v18, v0
	s_nop 1
	v_permlane32_swap_b32_e32 v0, v18
	v_add_f32_e32 v0, v0, v18
	v_fmamk_f32 v0, v0, 0x3a800000, v229
	v_cmp_gt_f32_e32 vcc, s87, v0
	v_mul_f32_e32 v18, 0x4f800000, v0
	s_nop 0
	v_cndmask_b32_e32 v0, v0, v18, vcc
	v_sqrt_f32_e32 v18, v0
	s_nop 0
	v_add_u32_e32 v19, -1, v18
	v_fma_f32 v20, -v19, v18, v0
	v_cmp_ge_f32_e64 s[38:39], 0, v20
	v_add_u32_e32 v20, 1, v18
	s_nop 0
	v_cndmask_b32_e64 v19, v18, v19, s[38:39]
	v_fma_f32 v18, -v20, v18, v0
	v_cmp_lt_f32_e64 s[38:39], 0, v18
	s_nop 1
	v_cndmask_b32_e64 v18, v19, v20, s[38:39]
	v_mul_f32_e32 v19, 0x37800000, v18
	v_cndmask_b32_e32 v18, v18, v19, vcc
	v_cmp_class_f32_e32 vcc, v0, v230
	s_nop 1
	v_cndmask_b32_e32 v0, v18, v0, vcc
	v_div_scale_f32 v18, s[0:1], v0, v0, 1.0
	v_rcp_f32_e32 v19, v18
	s_movk_i32 s0, 0x7fff
	v_fma_f32 v20, -v18, v19, 1.0
	v_fmac_f32_e32 v19, v20, v19
	v_div_scale_f32 v20, vcc, 1.0, v0, 1.0
	v_mul_f32_e32 v21, v20, v19
	v_fma_f32 v30, -v18, v21, v20
	v_fmac_f32_e32 v21, v30, v19
	v_fma_f32 v18, -v18, v21, v20
	v_div_fmas_f32 v18, v18, v19, v21
	v_div_fixup_f32 v0, v18, v0, 1.0
	v_lshlrev_b64 v[18:19], 11, v[22:23]
	v_lshl_add_u64 v[30:31], v[28:29], 0, v[18:19]
	global_load_dwordx4 v[18:21], v[26:27], off
	global_load_dwordx4 v[40:43], v[26:27], off offset:1024
	global_load_dwordx4 v[44:47], v[26:27], off offset:2048
	global_load_dwordx4 v[48:51], v[26:27], off offset:3072
	v_mul_f32_e32 v14, v14, v0
	v_mul_f32_e32 v15, v15, v0
	v_mul_f32_e32 v10, v10, v0
	v_mul_f32_e32 v11, v11, v0
	v_mul_f32_e32 v2, v2, v0
	v_mul_f32_e32 v3, v3, v0
	v_mul_f32_e32 v6, v6, v0
	v_add_u32_e32 v22, s94, v22
	v_cmp_lt_i32_e32 vcc, s0, v22
	s_or_b64 s[24:25], vcc, s[24:25]
	s_waitcnt vmcnt(0)
	v_mul_f32_e32 v14, v18, v14
	v_mul_f32_e32 v15, v19, v15
	v_cvt_pk_bf16_f32 v14, v14, v15
	v_mul_f32_e32 v15, v16, v0
	v_mul_f32_e32 v15, v20, v15
	v_mul_f32_e32 v16, v17, v0
	v_mul_f32_e32 v16, v21, v16
	v_cvt_pk_bf16_f32 v15, v15, v16
	global_store_dwordx2 v[30:31], v[14:15], off
	v_mul_f32_e32 v10, v40, v10
	v_mul_f32_e32 v11, v41, v11
	v_cvt_pk_bf16_f32 v10, v10, v11
	v_mul_f32_e32 v11, v12, v0
	v_mul_f32_e32 v11, v42, v11
	v_mul_f32_e32 v12, v13, v0
	v_mul_f32_e32 v12, v43, v12
	v_cvt_pk_bf16_f32 v11, v11, v12
	global_store_dwordx2 v[30:31], v[10:11], off offset:512
	v_mul_f32_e32 v2, v2, v44
	v_mul_f32_e32 v3, v3, v45
	v_cvt_pk_bf16_f32 v2, v2, v3
	v_mul_f32_e32 v3, v4, v0
	v_mul_f32_e32 v3, v3, v46
	v_mul_f32_e32 v4, v5, v0
	v_mul_f32_e32 v4, v4, v47
	v_cvt_pk_bf16_f32 v3, v3, v4
	global_store_dwordx2 v[30:31], v[2:3], off offset:1024
	v_mul_f32_e32 v2, v6, v48
	v_mul_f32_e32 v6, v7, v0
	v_mul_f32_e32 v3, v6, v49
	v_cvt_pk_bf16_f32 v2, v2, v3
	v_mul_f32_e32 v3, v8, v0
	v_mul_f32_e32 v3, v3, v50
	v_mul_f32_e32 v0, v9, v0
	v_mul_f32_e32 v0, v0, v51
	v_cvt_pk_bf16_f32 v3, v3, v0
	global_store_dwordx2 v[30:31], v[2:3], off offset:1536
	s_andn2_b64 exec, exec, s[24:25]
	s_cbranch_execnz .LBB0_517

.LBB0_820:
	v_ashrrev_i32_e32 v1, 31, v0
	v_lshlrev_b64 v[8:9], 12, v[0:1]
	v_lshl_add_u64 v[28:29], v[2:3], 0, v[8:9]
	global_load_dwordx4 v[8:11], v[28:29], off
	global_load_dwordx4 v[12:15], v[28:29], off offset:1024
	global_load_dwordx4 v[16:19], v[28:29], off offset:2048
	global_load_dwordx4 v[20:23], v[28:29], off offset:3072
	global_load_dwordx4 v[24:27], v[4:5], off
	global_load_dwordx4 v[40:43], v[4:5], off offset:1024
	global_load_dwordx4 v[44:47], v[4:5], off offset:2048
	global_load_dwordx4 v[48:51], v[4:5], off offset:3072
	v_add_u32_e32 v0, s94, v0
	s_waitcnt vmcnt(0)
	v_mul_f32_e32 v1, v9, v9
	v_mul_f32_e32 v30, v11, v11
	v_mul_f32_e32 v31, v13, v13
	v_mul_f32_e32 v32, v15, v15
	v_mul_f32_e32 v33, v17, v17
	v_mul_f32_e32 v34, v19, v19
	v_fmac_f32_e32 v1, v8, v8
	v_fmac_f32_e32 v30, v10, v10
	v_fmac_f32_e32 v31, v12, v12
	v_fmac_f32_e32 v32, v14, v14
	v_mul_f32_e32 v35, v21, v21
	v_mul_f32_e32 v36, v23, v23
	v_fmac_f32_e32 v33, v16, v16
	v_fmac_f32_e32 v34, v18, v18
	v_add_f32_e32 v1, v1, v30
	v_add_f32_e32 v30, v31, v32
	v_fmac_f32_e32 v35, v20, v20
	v_fmac_f32_e32 v36, v22, v22
	v_add_f32_e32 v31, v33, v34
	v_add_f32_e32 v1, v1, v30
	v_add_f32_e32 v32, v35, v36
	v_add_f32_e32 v1, v1, v31
	v_add_f32_e32 v1, v1, v32
	s_nop 1
	v_add_f32_dpp v1, v1, v1 quad_perm:[1,0,3,2] row_mask:0xf bank_mask:0xf
	s_nop 1
	v_add_f32_dpp v1, v1, v1 quad_perm:[2,3,0,1] row_mask:0xf bank_mask:0xf
	s_nop 1
	v_add_f32_dpp v1, v1, v1 row_half_mirror row_mask:0xf bank_mask:0xf
	s_nop 1
	v_add_f32_dpp v1, v1, v1 row_mirror row_mask:0xf bank_mask:0xf
	ds_swizzle_b32 v30, v1 offset:swizzle(SWAP,16)
	s_waitcnt lgkmcnt(0)
	v_add_f32_e32 v1, v1, v30
	v_mov_b32_e32 v30, v1
	s_nop 1
	v_permlane32_swap_b32_e32 v1, v30
	v_add_f32_e32 v1, v1, v30
	v_fmamk_f32 v1, v1, 0x3a800000, v6
	v_mul_f32_e32 v30, 0x4f800000, v1
	v_cmp_gt_f32_e32 vcc, s4, v1
	s_nop 1
	v_cndmask_b32_e32 v1, v1, v30, vcc
	v_sqrt_f32_e32 v30, v1
	s_nop 0
	v_add_u32_e32 v31, -1, v30
	v_add_u32_e32 v32, 1, v30
	v_fma_f32 v33, -v31, v30, v1
	v_fma_f32 v34, -v32, v30, v1
	v_cmp_ge_f32_e64 s[0:1], 0, v33
	s_nop 1
	v_cndmask_b32_e64 v30, v30, v31, s[0:1]
	v_cmp_lt_f32_e64 s[0:1], 0, v34
	s_nop 1
	v_cndmask_b32_e64 v30, v30, v32, s[0:1]
	v_mul_f32_e32 v31, 0x37800000, v30
	v_cndmask_b32_e32 v30, v30, v31, vcc
	v_cmp_class_f32_e32 vcc, v1, v7
	s_nop 1
	v_cndmask_b32_e32 v1, v30, v1, vcc
	v_div_scale_f32 v30, s[0:1], v1, v1, 1.0
	v_rcp_f32_e32 v31, v30
	v_div_scale_f32 v32, vcc, 1.0, v1, 1.0
	v_fma_f32 v33, -v30, v31, 1.0
	v_fmac_f32_e32 v31, v33, v31
	v_mul_f32_e32 v33, v32, v31
	v_fma_f32 v34, -v30, v33, v32
	v_fmac_f32_e32 v33, v34, v31
	v_fma_f32 v30, -v30, v33, v32
	v_div_fmas_f32 v30, v30, v31, v33
	v_div_fixup_f32 v30, v30, v1, 1.0
	v_pk_mul_f32 v[8:9], v[8:9], v[30:31] op_sel_hi:[1,0]
	v_pk_mul_f32 v[10:11], v[10:11], v[30:31] op_sel_hi:[1,0]
	v_pk_mul_f32 v[8:9], v[24:25], v[8:9]
	v_pk_mul_f32 v[10:11], v[26:27], v[10:11]
	global_store_dwordx4 v[28:29], v[8:11], off
	v_pk_mul_f32 v[14:15], v[14:15], v[30:31] op_sel_hi:[1,0]
	v_pk_mul_f32 v[12:13], v[12:13], v[30:31] op_sel_hi:[1,0]
	v_cmp_lt_i32_e32 vcc, s5, v0
	s_or_b64 s[2:3], vcc, s[2:3]
	v_pk_mul_f32 v[8:9], v[40:41], v[12:13]
	v_pk_mul_f32 v[10:11], v[42:43], v[14:15]
	global_store_dwordx4 v[28:29], v[8:11], off offset:1024
	v_pk_mul_f32 v[12:13], v[18:19], v[30:31] op_sel_hi:[1,0]
	v_pk_mul_f32 v[14:15], v[16:17], v[30:31] op_sel_hi:[1,0]
	v_pk_mul_f32 v[10:11], v[46:47], v[12:13]
	v_pk_mul_f32 v[8:9], v[44:45], v[14:15]
	global_store_dwordx4 v[28:29], v[8:11], off offset:2048
	v_pk_mul_f32 v[12:13], v[22:23], v[30:31] op_sel_hi:[1,0]
	v_pk_mul_f32 v[14:15], v[20:21], v[30:31] op_sel_hi:[1,0]
	v_pk_mul_f32 v[10:11], v[50:51], v[12:13]
	v_pk_mul_f32 v[8:9], v[48:49], v[14:15]
	global_store_dwordx4 v[28:29], v[8:11], off offset:3072
	s_andn2_b64 exec, exec, s[2:3]
	s_cbranch_execnz .LBB0_820
